# v3 + attention K staging: k_norm and rope loads issued together at the top of staging instead of 16 serialized load+vmcnt(0) pairs
# speedup vs baseline: 1.0243x; 1.0018x over previous
.LBB0_570:
	s_cmp_lg_u32 s46, 1
	s_cselect_b32 s0, s46, 0
	s_cmp_lg_u32 s46, 0
	s_cselect_b32 s47, s0, 1
	s_add_i32 s0, s47, s45
	s_cmp_lt_u32 s47, 3
	s_cselect_b64 s[20:21], -1, 0
	s_cmp_gt_u32 s0, 15
	s_cselect_b64 s[22:23], -1, 0
	s_and_b64 s[22:23], s[20:21], s[22:23]
	s_and_b64 vcc, exec, s[22:23]
	s_cbranch_vccnz .LBB0_632
	s_waitcnt lgkmcnt(0)
	s_barrier
	global_load_dwordx2 v[214:215], v[180:181], off
	global_load_dwordx2 v[216:217], v[180:181], off offset:8
	global_load_dwordx2 v[218:219], v[180:181], off offset:16
	global_load_dwordx2 v[220:221], v[180:181], off offset:24
	global_load_dwordx2 v[222:223], v[180:181], off offset:32
	global_load_dwordx2 v[224:225], v[180:181], off offset:40
	global_load_dwordx2 v[226:227], v[180:181], off offset:48
	global_load_dwordx2 v[228:229], v[180:181], off offset:56
	s_waitcnt vmcnt(10) lgkmcnt(2)
	s_andn2_b64 vcc, exec, s[20:21]
	s_cbranch_vccnz .Lat_norope_0
	v_lshl_or_b32 v246, s0, 7, v187
	v_ashrrev_i32_e32 v247, 31, v246
	v_lshlrev_b32_e32 v248, 2, v176
	v_lshlrev_b64 v[246:247], 8, v[246:247]
	v_mov_b32_e32 v249, v163
	v_lshl_add_u64 v[246:247], s[64:65], 0, v[246:247]
	v_lshl_add_u64 v[246:247], v[246:247], 0, v[248:249]
	global_load_dwordx2 v[230:231], v[246:247], off
	global_load_dwordx2 v[232:233], v[246:247], off offset:8
	global_load_dwordx2 v[234:235], v[246:247], off offset:16
	global_load_dwordx2 v[236:237], v[246:247], off offset:24
	global_load_dwordx2 v[238:239], v[246:247], off offset:32
	global_load_dwordx2 v[240:241], v[246:247], off offset:40
	global_load_dwordx2 v[242:243], v[246:247], off offset:48
	global_load_dwordx2 v[244:245], v[246:247], off offset:56
.Lat_norope_0:
	v_and_b32_e32 v145, 0xffff0000, v118
	v_lshlrev_b32_e32 v144, 16, v118
	v_and_b32_e32 v135, 0xffff0000, v119
	v_lshlrev_b32_e32 v134, 16, v119
	v_pk_mul_f32 v[146:147], v[144:145], v[144:145]
	v_pk_mul_f32 v[80:81], v[134:135], v[134:135]
	v_add_f32_e32 v146, v146, v147
	v_and_b32_e32 v79, 0xffff0000, v120
	v_lshlrev_b32_e32 v78, 16, v120
	v_add_f32_e32 v80, v80, v146
	s_waitcnt lgkmcnt(0)
	v_pk_mul_f32 v[130:131], v[78:79], v[78:79]
	v_add_f32_e32 v80, v81, v80
	v_and_b32_e32 v73, 0xffff0000, v121
	v_lshlrev_b32_e32 v72, 16, v121
	v_add_f32_e32 v80, v130, v80
	v_pk_mul_f32 v[132:133], v[72:73], v[72:73]
	v_add_f32_e32 v80, v131, v80
	v_and_b32_e32 v69, 0xffff0000, v114
	v_lshlrev_b32_e32 v68, 16, v114
	v_add_f32_e32 v80, v132, v80
	v_pk_mul_f32 v[136:137], v[68:69], v[68:69]
	v_add_f32_e32 v80, v133, v80
	v_and_b32_e32 v67, 0xffff0000, v115
	v_lshlrev_b32_e32 v66, 16, v115
	v_add_f32_e32 v80, v136, v80
	v_pk_mul_f32 v[138:139], v[66:67], v[66:67]
	v_add_f32_e32 v80, v137, v80
	v_and_b32_e32 v75, 0xffff0000, v116
	v_lshlrev_b32_e32 v74, 16, v116
	v_add_f32_e32 v80, v138, v80
	v_pk_mul_f32 v[140:141], v[74:75], v[74:75]
	v_add_f32_e32 v80, v139, v80
	v_and_b32_e32 v71, 0xffff0000, v117
	v_lshlrev_b32_e32 v70, 16, v117
	v_add_f32_e32 v80, v140, v80
	v_pk_mul_f32 v[142:143], v[70:71], v[70:71]
	v_add_f32_e32 v80, v141, v80
	v_add_f32_e32 v80, v142, v80
	v_add_f32_e32 v80, v143, v80
	ds_bpermute_b32 v81, v177, v80
	s_waitcnt lgkmcnt(0)
	v_add_f32_e32 v80, v80, v81
	ds_bpermute_b32 v81, v179, v80
	s_waitcnt lgkmcnt(0)
	v_add_f32_e32 v80, v80, v81
	v_fmamk_f32 v80, v80, 0x3c800000, v195
	v_mul_f32_e32 v81, 0x4f800000, v80
	v_cmp_gt_f32_e32 vcc, s31, v80
	s_nop 1
	v_cndmask_b32_e32 v81, v80, v81, vcc
	v_sqrt_f32_e32 v130, v81
	v_lshl_or_b32 v80, s0, 7, v187
	v_add_u32_e32 v131, -1, v130
	v_fma_f32 v132, -v131, v130, v81
	v_cmp_ge_f32_e64 s[0:1], 0, v132
	v_add_u32_e32 v132, 1, v130
	s_nop 0
	v_cndmask_b32_e64 v131, v130, v131, s[0:1]
	v_fma_f32 v130, -v132, v130, v81
	v_cmp_lt_f32_e64 s[0:1], 0, v130
	s_nop 1
	v_cndmask_b32_e64 v130, v131, v132, s[0:1]
	v_mul_f32_e32 v131, 0x37800000, v130
	v_cndmask_b32_e32 v130, v130, v131, vcc
	v_cmp_class_f32_e32 vcc, v81, v196
	s_nop 1
	v_cndmask_b32_e32 v130, v130, v81, vcc
	v_div_scale_f32 v131, s[0:1], v130, v130, 1.0
	v_rcp_f32_e32 v132, v131
	v_ashrrev_i32_e32 v81, 31, v80
	v_lshlrev_b64 v[80:81], 8, v[80:81]
	v_lshl_add_u64 v[80:81], s[64:65], 0, v[80:81]
	v_fma_f32 v133, -v131, v132, 1.0
	v_fmac_f32_e32 v132, v133, v132
	v_div_scale_f32 v133, vcc, 1.0, v130, 1.0
	v_mul_f32_e32 v136, v133, v132
	v_fma_f32 v137, -v131, v136, v133
	v_fmac_f32_e32 v136, v137, v132
	v_fma_f32 v131, -v131, v136, v133
	v_div_fmas_f32 v131, v131, v132, v136
	v_div_fixup_f32 v132, v131, v130, 1.0
	v_pk_mul_f32 v[130:131], v[132:133], v[144:145] op_sel_hi:[0,1]
	s_waitcnt vmcnt(0)
	v_pk_mul_f32 v[76:77], v[214:215], v[130:131]
	v_cndmask_b32_e64 v130, 0, 1, s[20:21]
	v_cmp_ne_u32_e64 s[0:1], 1, v130
	s_andn2_b64 vcc, exec, s[20:21]
	v_lshlrev_b32_e32 v130, 2, v176
	s_cbranch_vccnz .LBB0_573
	v_mov_b32_e32 v131, v163
	v_lshl_add_u64 v[136:137], v[80:81], 0, v[130:131]
	v_mov_b32_e32 v136, v230
	v_mov_b32_e32 v137, v231
	s_waitcnt vmcnt(0)
	v_pk_mul_f32 v[140:141], v[76:77], v[136:137] op_sel:[1,1] op_sel_hi:[1,0]
	v_pk_mul_f32 v[138:139], v[76:77], v[136:137]
	v_pk_fma_f32 v[76:77], v[76:77], v[136:137], v[140:141] op_sel_hi:[0,1,1]
	v_sub_f32_e32 v76, v138, v140
.LBB0_573:
	v_mov_b32_e32 v136, v216
	v_mov_b32_e32 v137, v217
	v_mov_b32_e32 v133, v132
	v_pk_mul_f32 v[134:135], v[132:133], v[134:135]
	s_and_b64 vcc, exec, s[0:1]
	s_waitcnt vmcnt(0)
	v_pk_mul_f32 v[134:135], v[134:135], v[136:137]
	s_cbranch_vccnz .LBB0_575
	v_mov_b32_e32 v131, v163
	v_lshl_add_u64 v[136:137], v[80:81], 0, v[130:131]
	v_mov_b32_e32 v136, v232
	v_mov_b32_e32 v137, v233
	s_waitcnt vmcnt(0)
	v_pk_mul_f32 v[140:141], v[134:135], v[136:137] op_sel:[1,1] op_sel_hi:[1,0]
	v_pk_mul_f32 v[138:139], v[134:135], v[136:137]
	v_pk_fma_f32 v[134:135], v[134:135], v[136:137], v[140:141] op_sel_hi:[0,1,1]
	v_sub_f32_e32 v134, v138, v140
.LBB0_575:
	v_mov_b32_e32 v136, v218
	v_mov_b32_e32 v137, v219
	v_pk_mul_f32 v[78:79], v[132:133], v[78:79]
	s_and_b64 vcc, exec, s[0:1]
	s_waitcnt vmcnt(0)
	v_pk_mul_f32 v[78:79], v[78:79], v[136:137]
	s_cbranch_vccnz .LBB0_577
	v_mov_b32_e32 v131, v163
	v_lshl_add_u64 v[136:137], v[80:81], 0, v[130:131]
	v_mov_b32_e32 v136, v234
	v_mov_b32_e32 v137, v235
	s_waitcnt vmcnt(0)
	v_pk_mul_f32 v[140:141], v[78:79], v[136:137] op_sel:[1,1] op_sel_hi:[1,0]
	v_pk_mul_f32 v[138:139], v[78:79], v[136:137]
	v_pk_fma_f32 v[78:79], v[78:79], v[136:137], v[140:141] op_sel_hi:[0,1,1]
	v_sub_f32_e32 v78, v138, v140
.LBB0_577:
	v_mov_b32_e32 v136, v220
	v_mov_b32_e32 v137, v221
	v_pk_mul_f32 v[72:73], v[132:133], v[72:73]
	s_and_b64 vcc, exec, s[0:1]
	s_waitcnt vmcnt(0)
	v_pk_mul_f32 v[72:73], v[72:73], v[136:137]
	s_cbranch_vccnz .LBB0_579
	v_mov_b32_e32 v131, v163
	v_lshl_add_u64 v[136:137], v[80:81], 0, v[130:131]
	v_mov_b32_e32 v136, v236
	v_mov_b32_e32 v137, v237
	s_waitcnt vmcnt(0)
	v_pk_mul_f32 v[140:141], v[72:73], v[136:137] op_sel:[1,1] op_sel_hi:[1,0]
	v_pk_mul_f32 v[138:139], v[72:73], v[136:137]
	v_pk_fma_f32 v[72:73], v[72:73], v[136:137], v[140:141] op_sel_hi:[0,1,1]
	v_sub_f32_e32 v72, v138, v140
.LBB0_579:
	v_mov_b32_e32 v136, v222
	v_mov_b32_e32 v137, v223
	v_pk_mul_f32 v[68:69], v[132:133], v[68:69]
	s_and_b64 vcc, exec, s[0:1]
	s_waitcnt vmcnt(0)
	v_pk_mul_f32 v[68:69], v[68:69], v[136:137]
	s_cbranch_vccnz .LBB0_581
	v_mov_b32_e32 v131, v163
	v_lshl_add_u64 v[136:137], v[80:81], 0, v[130:131]
	v_mov_b32_e32 v136, v238
	v_mov_b32_e32 v137, v239
	s_waitcnt vmcnt(0)
	v_pk_mul_f32 v[140:141], v[68:69], v[136:137] op_sel:[1,1] op_sel_hi:[1,0]
	v_pk_mul_f32 v[138:139], v[68:69], v[136:137]
	v_pk_fma_f32 v[68:69], v[68:69], v[136:137], v[140:141] op_sel_hi:[0,1,1]
	v_sub_f32_e32 v68, v138, v140
.LBB0_581:
	v_mov_b32_e32 v136, v224
	v_mov_b32_e32 v137, v225
	v_pk_mul_f32 v[66:67], v[132:133], v[66:67]
	s_and_b64 vcc, exec, s[0:1]
	s_waitcnt vmcnt(0)
	v_pk_mul_f32 v[66:67], v[66:67], v[136:137]
	s_cbranch_vccnz .LBB0_583
	v_mov_b32_e32 v131, v163
	v_lshl_add_u64 v[136:137], v[80:81], 0, v[130:131]
	v_mov_b32_e32 v136, v240
	v_mov_b32_e32 v137, v241
	s_waitcnt vmcnt(0)
	v_pk_mul_f32 v[140:141], v[66:67], v[136:137] op_sel:[1,1] op_sel_hi:[1,0]
	v_pk_mul_f32 v[138:139], v[66:67], v[136:137]
	v_pk_fma_f32 v[66:67], v[66:67], v[136:137], v[140:141] op_sel_hi:[0,1,1]
	v_sub_f32_e32 v66, v138, v140
.LBB0_583:
	v_mov_b32_e32 v136, v226
	v_mov_b32_e32 v137, v227
	v_pk_mul_f32 v[74:75], v[132:133], v[74:75]
	s_and_b64 vcc, exec, s[0:1]
	s_waitcnt vmcnt(0)
	v_pk_mul_f32 v[74:75], v[74:75], v[136:137]
	s_cbranch_vccnz .LBB0_585
	v_mov_b32_e32 v131, v163
	v_lshl_add_u64 v[136:137], v[80:81], 0, v[130:131]
	v_mov_b32_e32 v136, v242
	v_mov_b32_e32 v137, v243
	s_waitcnt vmcnt(0)
	v_pk_mul_f32 v[140:141], v[74:75], v[136:137] op_sel:[1,1] op_sel_hi:[1,0]
	v_pk_mul_f32 v[138:139], v[74:75], v[136:137]
	v_pk_fma_f32 v[74:75], v[74:75], v[136:137], v[140:141] op_sel_hi:[0,1,1]
	v_sub_f32_e32 v74, v138, v140
.LBB0_585:
	v_mov_b32_e32 v136, v228
	v_mov_b32_e32 v137, v229
	v_pk_mul_f32 v[70:71], v[132:133], v[70:71]
	s_and_b64 vcc, exec, s[0:1]
	s_waitcnt vmcnt(0)
	v_pk_mul_f32 v[70:71], v[70:71], v[136:137]
	s_cbranch_vccnz .LBB0_587
	v_mov_b32_e32 v131, v163
	v_lshl_add_u64 v[80:81], v[80:81], 0, v[130:131]
	v_mov_b32_e32 v80, v244
	v_mov_b32_e32 v81, v245
	s_waitcnt vmcnt(0)
	v_pk_mul_f32 v[132:133], v[70:71], v[80:81] op_sel:[1,1] op_sel_hi:[1,0]
	v_pk_mul_f32 v[130:131], v[70:71], v[80:81]
	v_pk_fma_f32 v[70:71], v[70:71], v[80:81], v[132:133] op_sel_hi:[0,1,1]
	v_sub_f32_e32 v70, v130, v132

.LBB0_942:
	s_cmp_lg_u32 s45, 1
	s_cselect_b32 s0, s45, 0
	s_cmp_lg_u32 s45, 0
	s_cselect_b32 s46, s0, 1
	s_add_i32 s0, s46, s43
	s_cmp_lt_u32 s46, 3
	s_cselect_b64 s[20:21], -1, 0
	s_cmp_gt_u32 s0, 15
	s_cselect_b64 s[22:23], -1, 0
	s_and_b64 s[22:23], s[20:21], s[22:23]
	s_and_b64 vcc, exec, s[22:23]
	s_cbranch_vccnz .LBB0_1004
	s_waitcnt lgkmcnt(0)
	s_barrier
	global_load_dwordx2 v[214:215], v[180:181], off
	global_load_dwordx2 v[216:217], v[180:181], off offset:8
	global_load_dwordx2 v[218:219], v[180:181], off offset:16
	global_load_dwordx2 v[220:221], v[180:181], off offset:24
	global_load_dwordx2 v[222:223], v[180:181], off offset:32
	global_load_dwordx2 v[224:225], v[180:181], off offset:40
	global_load_dwordx2 v[226:227], v[180:181], off offset:48
	global_load_dwordx2 v[228:229], v[180:181], off offset:56
	s_waitcnt vmcnt(10) lgkmcnt(2)
	s_andn2_b64 vcc, exec, s[20:21]
	s_cbranch_vccnz .Lat_norope_1
	v_lshl_or_b32 v246, s0, 7, v187
	v_ashrrev_i32_e32 v247, 31, v246
	v_lshlrev_b32_e32 v248, 2, v176
	v_lshlrev_b64 v[246:247], 8, v[246:247]
	v_mov_b32_e32 v249, v163
	v_lshl_add_u64 v[246:247], s[8:9], 0, v[246:247]
	v_lshl_add_u64 v[246:247], v[246:247], 0, v[248:249]
	global_load_dwordx2 v[230:231], v[246:247], off
	global_load_dwordx2 v[232:233], v[246:247], off offset:8
	global_load_dwordx2 v[234:235], v[246:247], off offset:16
	global_load_dwordx2 v[236:237], v[246:247], off offset:24
	global_load_dwordx2 v[238:239], v[246:247], off offset:32
	global_load_dwordx2 v[240:241], v[246:247], off offset:40
	global_load_dwordx2 v[242:243], v[246:247], off offset:48
	global_load_dwordx2 v[244:245], v[246:247], off offset:56
.Lat_norope_1:
	v_and_b32_e32 v145, 0xffff0000, v118
	v_lshlrev_b32_e32 v144, 16, v118
	v_and_b32_e32 v135, 0xffff0000, v119
	v_lshlrev_b32_e32 v134, 16, v119
	v_pk_mul_f32 v[146:147], v[144:145], v[144:145]
	v_pk_mul_f32 v[80:81], v[134:135], v[134:135]
	v_add_f32_e32 v146, v146, v147
	v_and_b32_e32 v79, 0xffff0000, v120
	v_lshlrev_b32_e32 v78, 16, v120
	v_add_f32_e32 v80, v80, v146
	s_waitcnt lgkmcnt(0)
	v_pk_mul_f32 v[130:131], v[78:79], v[78:79]
	v_add_f32_e32 v80, v81, v80
	v_and_b32_e32 v73, 0xffff0000, v121
	v_lshlrev_b32_e32 v72, 16, v121
	v_add_f32_e32 v80, v130, v80
	v_pk_mul_f32 v[132:133], v[72:73], v[72:73]
	v_add_f32_e32 v80, v131, v80
	v_and_b32_e32 v69, 0xffff0000, v114
	v_lshlrev_b32_e32 v68, 16, v114
	v_add_f32_e32 v80, v132, v80
	v_pk_mul_f32 v[136:137], v[68:69], v[68:69]
	v_add_f32_e32 v80, v133, v80
	v_and_b32_e32 v67, 0xffff0000, v115
	v_lshlrev_b32_e32 v66, 16, v115
	v_add_f32_e32 v80, v136, v80
	v_pk_mul_f32 v[138:139], v[66:67], v[66:67]
	v_add_f32_e32 v80, v137, v80
	v_and_b32_e32 v75, 0xffff0000, v116
	v_lshlrev_b32_e32 v74, 16, v116
	v_add_f32_e32 v80, v138, v80
	v_pk_mul_f32 v[140:141], v[74:75], v[74:75]
	v_add_f32_e32 v80, v139, v80
	v_and_b32_e32 v71, 0xffff0000, v117
	v_lshlrev_b32_e32 v70, 16, v117
	v_add_f32_e32 v80, v140, v80
	v_pk_mul_f32 v[142:143], v[70:71], v[70:71]
	v_add_f32_e32 v80, v141, v80
	v_add_f32_e32 v80, v142, v80
	v_add_f32_e32 v80, v143, v80
	ds_bpermute_b32 v81, v177, v80
	s_waitcnt lgkmcnt(0)
	v_add_f32_e32 v80, v80, v81
	ds_bpermute_b32 v81, v179, v80
	s_waitcnt lgkmcnt(0)
	v_add_f32_e32 v80, v80, v81
	v_fmamk_f32 v80, v80, 0x3c800000, v195
	v_mul_f32_e32 v81, 0x4f800000, v80
	v_cmp_gt_f32_e32 vcc, s30, v80
	s_nop 1
	v_cndmask_b32_e32 v81, v80, v81, vcc
	v_sqrt_f32_e32 v130, v81
	v_lshl_or_b32 v80, s0, 7, v187
	v_add_u32_e32 v131, -1, v130
	v_fma_f32 v132, -v131, v130, v81
	v_cmp_ge_f32_e64 s[0:1], 0, v132
	v_add_u32_e32 v132, 1, v130
	s_nop 0
	v_cndmask_b32_e64 v131, v130, v131, s[0:1]
	v_fma_f32 v130, -v132, v130, v81
	v_cmp_lt_f32_e64 s[0:1], 0, v130
	s_nop 1
	v_cndmask_b32_e64 v130, v131, v132, s[0:1]
	v_mul_f32_e32 v131, 0x37800000, v130
	v_cndmask_b32_e32 v130, v130, v131, vcc
	v_cmp_class_f32_e32 vcc, v81, v196
	s_nop 1
	v_cndmask_b32_e32 v130, v130, v81, vcc
	v_div_scale_f32 v131, s[0:1], v130, v130, 1.0
	v_rcp_f32_e32 v132, v131
	v_ashrrev_i32_e32 v81, 31, v80
	v_lshlrev_b64 v[80:81], 8, v[80:81]
	v_lshl_add_u64 v[80:81], s[8:9], 0, v[80:81]
	v_fma_f32 v133, -v131, v132, 1.0
	v_fmac_f32_e32 v132, v133, v132
	v_div_scale_f32 v133, vcc, 1.0, v130, 1.0
	v_mul_f32_e32 v136, v133, v132
	v_fma_f32 v137, -v131, v136, v133
	v_fmac_f32_e32 v136, v137, v132
	v_fma_f32 v131, -v131, v136, v133
	v_div_fmas_f32 v131, v131, v132, v136
	v_div_fixup_f32 v132, v131, v130, 1.0
	v_pk_mul_f32 v[130:131], v[132:133], v[144:145] op_sel_hi:[0,1]
	s_waitcnt vmcnt(0)
	v_pk_mul_f32 v[76:77], v[214:215], v[130:131]
	v_cndmask_b32_e64 v130, 0, 1, s[20:21]
	v_cmp_ne_u32_e64 s[0:1], 1, v130
	s_andn2_b64 vcc, exec, s[20:21]
	v_lshlrev_b32_e32 v130, 2, v176
	s_cbranch_vccnz .LBB0_945
	v_mov_b32_e32 v131, v163
	v_lshl_add_u64 v[136:137], v[80:81], 0, v[130:131]
	v_mov_b32_e32 v136, v230
	v_mov_b32_e32 v137, v231
	s_waitcnt vmcnt(0)
	v_pk_mul_f32 v[140:141], v[76:77], v[136:137] op_sel:[1,1] op_sel_hi:[1,0]
	v_pk_mul_f32 v[138:139], v[76:77], v[136:137]
	v_pk_fma_f32 v[76:77], v[76:77], v[136:137], v[140:141] op_sel_hi:[0,1,1]
	v_sub_f32_e32 v76, v138, v140
